# grid barriers after phases 7 and 15 replaced by completion counters (only the sample split-K units / sample cross units depend on those phases)
# baseline (speedup 1.0000x reference)
; __device__ __forceinline__ unsigned xb_ld(unsigned* p)              { return __hip_atomic_load(p, __ATOMIC_RELAXED, __HIP_MEMORY_SCOPE_AGENT); }
; __device__ __forceinline__ unsigned xb_add(unsigned* p, unsigned v) { return __hip_atomic_fetch_add(p, v, __ATOMIC_RELAXED, __HIP_MEMORY_SCOPE_AGENT); }
; #define CASE(k) if (PH_ON(k) && ph_lo <= (k) && (k) < ph_hi)
; #define SEAM(k) if (ph_lo <= (k) && (k) < ph_hi && ph_hi - ph_lo > 1) xcd_barrier(bar);
; __device__ __forceinline__ void xcd_barrier(const XcdBarrier& b) {
;     asm volatile("s_waitcnt vmcnt(0)" ::: "memory");
;     __syncthreads();
;     if (threadIdx.x == 0) {
;         unsigned* bar = b.bar;
;         __builtin_amdgcn_s_waitcnt(0);
;         unsigned nloc = b.st[0], nx = b.st[1];
;         if (nloc == 0u) { xcd_barrier_complete(bar, b.x, nloc, nx); b.st[0] = nloc; b.st[1] = nx; }
;         const unsigned old = xb_add(&bar[XB_XSUB(b.x)], 1u);
;         const unsigned gen = old / nloc;
;         if (old + 1u == (gen + 1u) * nloc) {
;             __builtin_amdgcn_fence(__ATOMIC_RELEASE, "agent");
;             asm volatile("s_waitcnt vmcnt(0)" ::: "memory");
;             const unsigned og = xb_add(&bar[XB_TOP], 1u);
;             const unsigned tg = og / nx;
;             if (og + 1u == (tg + 1u) * nx) xb_add(&bar[XB_TOPGEN], 1u);
;             else XB_SPIN(xb_ld(&bar[XB_TOPGEN]) == tg, bar);
;             __builtin_amdgcn_fence(__ATOMIC_ACQUIRE, "agent");
;             xb_add(&bar[XB_XGEN(b.x)], 1u);
;             asm volatile("s_waitcnt vmcnt(0)" ::: "memory");
;         } else {
;             XB_SPIN(xb_ld(&bar[XB_XGEN(b.x)]) == gen, bar);
;             __builtin_amdgcn_fence(__ATOMIC_ACQUIRE, "agent");
;             asm volatile("s_waitcnt vmcnt(0)" ::: "memory");
;         }
;     }
;     __syncthreads();
; }
; __global__ void __launch_bounds__(512, 2) mega(Params p) {
;     ...
;         CASE(7) sample_reduce<0>((const float*)(ws + O_SLAB), 4, nullptr, nullptr, 1.f, (const float*)(ws + O_ST1), p.in[9], p.in[10], XB, (float*)(ws + O_ST2), nullptr, nullptr, XB); SEAM(7)
;         CASE(8) { pg8::Gemm g{XB, (const bf16_t*)(ws + O_WQ), NP, D, D, D}; pg8::StaticOrder S; S.init(NP, D, G, bx); pg8::EpiBf16 E{(bf16_t*)(ws + O_QC), D, 0.0625f * LOG2E, (const float*)(ws + O_ST2), (const float*)(ws + O_C1) + C_Q, (const float*)(ws + O_C2) + C_Q};
.LBB0_1132:
	s_or_b64 exec, exec, s[12:13]
	v_readlane_b32 s0, v252, 12
	v_readlane_b32 s1, v252, 13
	s_andn2_b64 vcc, exec, s[0:1]
	s_cbranch_vccnz .LBB0_1178
	s_waitcnt vmcnt(0) lgkmcnt(0)
	s_barrier
	s_cmpk_gt_u32 s2, 0x7f
	s_cbranch_scc1 .Lq7_prod_done
	s_mov_b64 s[38:39], exec
	v_readlane_b32 s0, v252, 6
	v_readlane_b32 s1, v252, 7
	s_and_b64 s[0:1], s[38:39], s[0:1]
	s_mov_b64 exec, s[0:1]
	s_cbranch_execz .Lq7_prod_restore
	buffer_wbl2 sc1
	s_waitcnt vmcnt(0)
	s_add_u32 s98, s52, 0x2fb46840
	s_addc_u32 s99, s53, 0
	v_mov_b32_e32 v0, 0
	v_mov_b32_e32 v1, 1
	global_atomic_add v0, v1, s[98:99]
	s_waitcnt vmcnt(0)
.Lq7_prod_restore:
	s_mov_b64 exec, s[38:39]
.Lq7_prod_done:
	s_branch .LBB0_1178
	s_waitcnt vmcnt(0)
	s_waitcnt vmcnt(0) lgkmcnt(0)
	s_barrier
	s_mov_b64 s[38:39], exec
	v_readlane_b32 s0, v252, 6
	v_readlane_b32 s1, v252, 7
	s_and_b64 s[0:1], s[38:39], s[0:1]
	s_mov_b64 exec, s[0:1]
	s_cbranch_execz .LBB0_1177
	s_add_i32 s0, 0, 0x23f10
	v_mov_b32_e32 v0, s0
	s_waitcnt vmcnt(0) expcnt(0) lgkmcnt(0)
	ds_read_b32 v2, v0
	s_add_i32 s0, 0, 0x23f14
	v_mov_b32_e32 v0, s0
	ds_read_b32 v0, v0
	s_waitcnt lgkmcnt(1)
	v_cmp_ne_u32_e32 vcc, 0, v2
	s_cbranch_vccnz .LBB0_1148
	s_add_u32 s6, s52, 0x2fb43200
	s_addc_u32 s7, s53, 0
	s_add_u32 s4, s52, 0x2fb43400
	s_addc_u32 s5, s53, 0
	s_add_u32 s10, s52, 0x2fb43500
	s_addc_u32 s11, s53, 0
	s_add_u32 s12, s52, 0x2fb43600
	s_addc_u32 s13, s53, 0
	s_add_u32 s14, s52, 0x2fb43700
	s_addc_u32 s15, s53, 0
	s_add_u32 s16, s52, 0x2fb43800
	s_addc_u32 s17, s53, 0
	s_add_u32 s18, s52, 0x2fb43900
	s_addc_u32 s19, s53, 0
	s_add_u32 s20, s52, 0x2fb43a00
	s_addc_u32 s21, s53, 0
	s_add_u32 s22, s52, 0x2fb43b00
	s_addc_u32 s23, s53, 0
	s_add_u32 s24, s52, 0x2fb43c00
	s_addc_u32 s25, s53, 0
	s_add_u32 s26, s52, 0x2fb43d00
	s_addc_u32 s27, s53, 0
	s_add_u32 s28, s52, 0x2fb43e00
	s_addc_u32 s29, s53, 0
	s_add_u32 s30, s52, 0x2fb43f00
	s_addc_u32 s31, s53, 0
	s_add_u32 s34, s52, 0x2fb44000
	s_addc_u32 s35, s53, 0
	s_add_u32 s36, s52, 0x2fb44100
	s_addc_u32 s37, s53, 0
	s_add_u32 s40, s52, 0x2fb44200
	s_addc_u32 s41, s53, 0
	v_readlane_b32 s0, v252, 0
	s_add_u32 s46, s52, 0x2fb44300
	s_mul_i32 s0, s83, s0
	s_addc_u32 s47, s53, 0
	s_mul_i32 s0, s0, s82
	s_mov_b32 s1, 1
	s_mov_b64 s[8:9], 0
	s_waitcnt lgkmcnt(0)
	v_mov_b64_e32 v[0:1], s[4:5]
	v_mov_b64_e32 v[2:3], s[10:11]
	v_mov_b64_e32 v[4:5], s[12:13]
	v_mov_b64_e32 v[6:7], s[14:15]
	v_mov_b64_e32 v[8:9], s[16:17]
	v_mov_b64_e32 v[10:11], s[18:19]
	v_mov_b64_e32 v[12:13], s[20:21]
	v_mov_b64_e32 v[14:15], s[22:23]
	v_mov_b64_e32 v[16:17], s[24:25]
	v_mov_b64_e32 v[18:19], s[26:27]
	v_mov_b64_e32 v[20:21], s[28:29]
	v_mov_b64_e32 v[22:23], s[30:31]
	v_mov_b64_e32 v[24:25], s[34:35]
	v_mov_b64_e32 v[26:27], s[36:37]
	v_mov_b64_e32 v[28:29], s[40:41]
	v_mov_b64_e32 v[30:31], s[46:47]
	s_branch .LBB0_1138

; template <class Epi, class Sched, bool ALIGN_EPI = false, bool SP2 = false>
; __device__ __forceinline__ void gemm_phase(LAS unsigned char* lds, const Gemm g, const Sched& S, const Epi& E) {
;     ...
;     const int wid = __builtin_amdgcn_readfirstlane(tid >> 6), lane = tid & 63, wr = wid >> 2, wc = wid & 3, fr = lane & 15, fq = lane >> 4;
;     const int K = g.ldk, nt = g.K / BK;
;     unsigned voffA[2], voffB[2];
; #pragma unroll
;     for (int i = 0; i < 2; ++i) { int R, C; stage_rc(tid * 16 + i * 8192, R, C); const int Rb = Epi::PERM ? ((R & ~31) + perm32(R & 31)) : R;
;         voffA[i] = (unsigned)(R * K + C) * 2u; voffB[i] = (unsigned)(Rb * K + C) * 2u; }
;     const size_t kstep = (size_t)(BK * 2);
;     const size_t hstep = (size_t)HALF * K * 2;
;     const size_t tstep = 2 * hstep;
;     const unsigned ldsw = (unsigned)wid * 1024u;
;     const int aoff = lds_byte(wr * 64 + fr, fq * 8), boff = lds_byte(wc * 32 + fr, fq * 8);
;     ...
;     Unit cur, nxt; int ui = 0;
;     if (!S.next(0, cur)) return;
;     f32x4 acc[2][2][4][2];
; #pragma unroll
;     for (int a = 0; a < 2; ++a)
; #pragma unroll
;         for (int b = 0; b < 2; ++b)
; #pragma unroll
;             for (int m = 0; m < 4; ++m)
; #pragma unroll
;                 for (int n = 0; n < 2; ++n) acc[a][b][m][n] = (f32x4){0.f, 0.f, 0.f, 0.f};
;     bf16x8 At[4][2], B0[2][2], B1[2][2];
;     const char* cA = (const char*)g.A + (size_t)cur.pm * tstep + (size_t)cur.kofs * 2; const char* cB = (const char*)g.Bt + (size_t)cur.pn * tstep + (size_t)cur.kofs * 2;
;     if constexpr (SP2) {
;         PG8_STAGE(PG8_SB(0, 0), cB, voffB); PG8_STAGE(PG8_SB(0, 1), cB + hstep, voffB); PG8_STAGE(PG8_SA(0, 0), cA, voffA); PG8_STAGE(PG8_SA(0, 1), cA + hstep, voffA);
;         if (wr == 1) PG8_BAR;
;         PG8_WAIT_V(2); PG8_BAR;
;         PG8_STAGE(PG8_SB(1, 0), cB + kstep, voffB); PG8_STAGE(PG8_SA(1, 0), cA + kstep, voffA); PG8_STAGE(PG8_SB(1, 1), cB + hstep + kstep, voffB);
;         PG8_WAIT_V(6); PG8_BAR;
;     } else {
;         PG8_STAGE(PG8_SB(0, 0), cB, voffB); PG8_STAGE(PG8_SA(0, 0), cA, voffA); PG8_STAGE(PG8_SB(0, 1), cB + hstep, voffB); PG8_STAGE(PG8_SA(0, 1), cA + hstep, voffA);
;         if (wr == 1) PG8_BAR;
;         PG8_WAIT_V(4); PG8_BAR;
;         PG8_STAGE(PG8_SB(1, 0), cB + kstep, voffB); PG8_STAGE(PG8_SA(1, 0), cA + kstep, voffA); PG8_STAGE(PG8_SB(1, 1), cB + hstep + kstep, voffB);
.LBB0_1207:
	v_mov_b32_e32 v8, v208
	s_cmp_gt_i32 s2, 63
	v_readfirstlane_b32 s6, v8
	s_cbranch_scc1 .LBB0_1225
	s_add_u32 s98, s52, 0x2fb46840
	s_addc_u32 s99, s53, 0
	s_mov_b32 s101, 0
	v_mov_b32_e32 v0, 0
.Lq7_spin:
	global_load_dword v1, v0, s[98:99] sc1
	s_waitcnt vmcnt(0)
	v_readfirstlane_b32 s100, v1
	s_cmpk_gt_u32 s100, 0x7f
	s_cbranch_scc1 .Lq7_ready
	s_sleep 2
	s_add_i32 s101, s101, 1
	s_cmp_lt_u32 s101, 0x2000
	s_cbranch_scc1 .Lq7_spin
.Lq7_ready:
	buffer_inv sc1
	s_waitcnt vmcnt(0)
	v_lshlrev_b32_e32 v0, 4, v8
	v_add_u32_e32 v1, 0x2000, v0
	s_waitcnt lgkmcnt(0)
	v_ashrrev_i32_e32 v2, 31, v1
	v_lshrrev_b32_e32 v2, 22, v2
	v_add_u32_e32 v2, v1, v2
	v_ashrrev_i32_e32 v2, 10, v2
	v_mul_i32_i24_e32 v3, 0x400, v2
	v_sub_u32_e32 v1, v1, v3
	v_lshrrev_b32_e32 v3, 4, v1
	v_bitop3_b32 v1, v3, v1, 32 bitop3:0x6c
	v_ashrrev_i32_e32 v3, 31, v1
	v_lshrrev_b32_e32 v3, 26, v3
	v_add_u32_e32 v3, v1, v3
	v_lshrrev_b32_e32 v4, 6, v3
	v_lshlrev_b32_e32 v5, 3, v2
	v_and_b32_e32 v3, 0xc0, v3
	v_and_b32_e32 v5, 0x1ffff0, v5
	v_lshlrev_b32_e32 v2, 5, v2
	v_sub_u32_e32 v1, v1, v3
	v_mov_b32_e32 v3, 1
	v_add_u32_e32 v4, v4, v5
	v_and_b32_e32 v2, 32, v2
	v_ashrrev_i16_sdwa v1, v3, sext(v1) dst_sel:DWORD dst_unused:UNUSED_PAD src0_sel:DWORD src1_sel:BYTE_0
	v_lshl_or_b32 v2, v4, 10, v2
	v_bfe_i32 v1, v1, 0, 16
	v_add_lshl_u32 v128, v2, v1, 1
	v_bfe_i32 v1, v8, 27, 1
	v_lshrrev_b32_e32 v1, 22, v1
	v_add_u32_e32 v1, v0, v1
	v_and_b32_e32 v1, 0xfffffc00, v1
	s_lshr_b32 s5, s3, 30
	v_sub_u32_e32 v0, v0, v1
	s_add_i32 s5, s2, s5
	v_lshrrev_b32_e32 v1, 4, v0
	s_ashr_i32 s8, s5, 2
	s_ashr_i32 s5, s5, 4
	v_bitop3_b32 v0, v1, v0, 32 bitop3:0x6c
	v_ashrrev_i32_e32 v4, 31, v8
	s_add_i32 s12, s5, 0x80
	s_and_b32 s46, s8, 3
	s_lshl_b32 s5, s8, 10
	s_lshl_b32 s8, s2, 8
	v_ashrrev_i32_e32 v1, 31, v0
	v_lshrrev_b32_e32 v4, 26, v4
	s_sub_i32 s14, s8, s5
	s_ashr_i32 s7, s6, 6
	v_lshrrev_b32_e32 v1, 26, v1
	v_add_u32_e32 v4, v8, v4
	s_ashr_i32 s13, s12, 31
	s_ashr_i32 s15, s14, 31
	s_ashr_i32 s10, s6, 8
	s_lshl_b32 s4, s7, 10
	v_add_u32_e32 v1, v0, v1
	v_ashrrev_i32_e32 v4, 6, v4
	s_lshl_b64 s[8:9], s[12:13], 19
	s_lshl_b64 s[16:17], s[14:15], 1
	s_lshl_b32 s5, s46, 19
	v_lshrrev_b32_e32 v2, 6, v1
	v_lshlrev_b32_e32 v5, 3, v4
	v_and_b32_e32 v1, 0xc0, v1
	s_add_u32 s5, s0, s5
	v_and_b32_e32 v5, 0x1ffff0, v5
	v_lshlrev_b32_e32 v4, 5, v4
	v_sub_u32_e32 v0, v0, v1
	s_addc_u32 s11, s1, 0
	v_add_u32_e32 v2, v2, v5
	v_and_b32_e32 v4, 32, v4
	v_ashrrev_i16_sdwa v0, v3, sext(v0) dst_sel:DWORD dst_unused:UNUSED_PAD src0_sel:DWORD src1_sel:BYTE_0
	s_add_u32 s36, s5, s16
	v_lshl_or_b32 v2, v2, 10, v4
	v_bfe_i32 v0, v0, 0, 16
	s_addc_u32 s37, s11, s17
	s_add_i32 s5, s4, 0
	v_add_lshl_u32 v130, v2, v0, 1
	s_add_i32 m0, s5, 0x10000
	v_mov_b32_e32 v131, 0
	global_load_lds_dwordx4 v130, s[36:37]
	s_add_i32 m0, s5, 0x12000
	s_add_u32 s11, s42, s8
	s_addc_u32 s13, s43, s9
	s_add_u32 s8, s36, 0x40000
	global_load_lds_dwordx4 v128, s[36:37]
	s_addc_u32 s9, s37, 0
	s_add_i32 m0, s5, 0x14000
	v_mov_b32_e32 v129, v131
	global_load_lds_dwordx4 v130, s[8:9]
	s_add_i32 m0, s5, 0x16000
	s_add_u32 s34, s11, s16
	s_addc_u32 s35, s13, s17
	s_add_i32 s13, s5, 0x2000
	global_load_lds_dwordx4 v128, s[8:9]
	s_mov_b32 m0, s5
	s_add_u32 s8, s34, 0x40000
	global_load_lds_dwordx4 v130, s[34:35]
	s_mov_b32 m0, s13
	s_addc_u32 s9, s35, 0
	s_add_i32 s15, s5, 0x4000
	global_load_lds_dwordx4 v128, s[34:35]
	s_mov_b32 m0, s15
	s_add_i32 s33, s5, 0x6000
	global_load_lds_dwordx4 v130, s[8:9]
	s_mov_b32 m0, s33
	s_cmp_eq_u32 s10, 1
	global_load_lds_dwordx4 v128, s[8:9]
	v_lshl_add_u64 v[6:7], s[36:37], 0, v[130:131]
	v_lshl_add_u64 v[4:5], s[36:37], 0, v[128:129]
	v_lshl_add_u64 v[0:1], s[34:35], 0, v[130:131]
	s_cselect_b64 s[8:9], -1, 0
	s_cmp_lg_u32 s10, 1
	v_lshl_add_u64 v[2:3], s[34:35], 0, v[128:129]
	s_cbranch_scc1 .LBB0_1210
	s_barrier

; __device__ __forceinline__ unsigned xb_add(unsigned* p, unsigned v) { return __hip_atomic_fetch_add(p, v, __ATOMIC_RELAXED, __HIP_MEMORY_SCOPE_AGENT); }
; #define CASE(k) if (PH_ON(k) && ph_lo <= (k) && (k) < ph_hi)
; #define SEAM(k) if (ph_lo <= (k) && (k) < ph_hi && ph_hi - ph_lo > 1) xcd_barrier(bar);
; __device__ __forceinline__ void xcd_barrier(const XcdBarrier& b) {
;     asm volatile("s_waitcnt vmcnt(0)" ::: "memory");
;     __syncthreads();
;     if (threadIdx.x == 0) {
;         unsigned* bar = b.bar;
;         __builtin_amdgcn_s_waitcnt(0);
;         unsigned nloc = b.st[0], nx = b.st[1];
;         if (nloc == 0u) { xcd_barrier_complete(bar, b.x, nloc, nx); b.st[0] = nloc; b.st[1] = nx; }
;         const unsigned old = xb_add(&bar[XB_XSUB(b.x)], 1u);
;         const unsigned gen = old / nloc;
;         if (old + 1u == (gen + 1u) * nloc) {
;             __builtin_amdgcn_fence(__ATOMIC_RELEASE, "agent");
; __global__ void __launch_bounds__(512, 2) mega(Params p) {
;     ...
;         CASE(15) sample_reduce<1>((const float*)(ws + O_SLAB), 4, nullptr, nullptr, 0.0625f * LOG2E, (const float*)(ws + O_ST2), nullptr, nullptr, (bf16_t*)(ws + O_QC), nullptr, (const float*)(ws + O_C1) + C_Q, (const float*)(ws + O_C2) + C_Q); SEAM(15)
;         for (int rep9 = 0; rep9 <= REP9; ++rep9)
.LBB0_1274:
	s_or_b64 exec, exec, s[8:9]
	v_readlane_b32 s0, v252, 12
	v_readlane_b32 s1, v252, 13
	s_andn2_b64 vcc, exec, s[0:1]
	s_cbranch_vccnz .LBB0_1320
	s_waitcnt vmcnt(0) lgkmcnt(0)
	s_barrier
	s_cmpk_gt_u32 s2, 0x7f
	s_cbranch_scc1 .Lq15_prod_done
	s_mov_b64 s[38:39], exec
	v_readlane_b32 s0, v252, 6
	v_readlane_b32 s1, v252, 7
	s_and_b64 s[0:1], s[38:39], s[0:1]
	s_mov_b64 exec, s[0:1]
	s_cbranch_execz .Lq15_prod_restore
	buffer_wbl2 sc1
	s_waitcnt vmcnt(0)
	s_add_u32 s98, s52, 0x2fb46800
	s_addc_u32 s99, s53, 0
	v_mov_b32_e32 v0, 0
	v_mov_b32_e32 v1, 1
	global_atomic_add v0, v1, s[98:99]
	s_waitcnt vmcnt(0)

; __device__ __forceinline__ unsigned xb_ld(unsigned* p)              { return __hip_atomic_load(p, __ATOMIC_RELAXED, __HIP_MEMORY_SCOPE_AGENT); }
; __device__ __forceinline__ unsigned xb_add(unsigned* p, unsigned v) { return __hip_atomic_fetch_add(p, v, __ATOMIC_RELAXED, __HIP_MEMORY_SCOPE_AGENT); }
; #define XB_SPIN(cond, bar) do { unsigned _sp = 0; while (cond) { __builtin_amdgcn_s_sleep(1); \
;     if ((++_sp & 255u) == 0u) { if (xb_ld(&(bar)[XB_TMO])) break; if (_sp > XB_SPIN_CAP) { atomicAdd(&(bar)[XB_TMO], 1u); break; } } } } while (0)
; #define CASE(k) if (PH_ON(k) && ph_lo <= (k) && (k) < ph_hi)
; #define SEAM(k) if (ph_lo <= (k) && (k) < ph_hi && ph_hi - ph_lo > 1) xcd_barrier(bar);
; __device__ __forceinline__ void xcd_barrier(const XcdBarrier& b) {
;     asm volatile("s_waitcnt vmcnt(0)" ::: "memory");
;     __syncthreads();
;     if (threadIdx.x == 0) {
;         unsigned* bar = b.bar;
;         __builtin_amdgcn_s_waitcnt(0);
;         unsigned nloc = b.st[0], nx = b.st[1];
;         if (nloc == 0u) { xcd_barrier_complete(bar, b.x, nloc, nx); b.st[0] = nloc; b.st[1] = nx; }
;         const unsigned old = xb_add(&bar[XB_XSUB(b.x)], 1u);
;         const unsigned gen = old / nloc;
;         if (old + 1u == (gen + 1u) * nloc) {
;             __builtin_amdgcn_fence(__ATOMIC_RELEASE, "agent");
;             asm volatile("s_waitcnt vmcnt(0)" ::: "memory");
;             const unsigned og = xb_add(&bar[XB_TOP], 1u);
;             const unsigned tg = og / nx;
;             if (og + 1u == (tg + 1u) * nx) xb_add(&bar[XB_TOPGEN], 1u);
;             else XB_SPIN(xb_ld(&bar[XB_TOPGEN]) == tg, bar);
;             __builtin_amdgcn_fence(__ATOMIC_ACQUIRE, "agent");
;             xb_add(&bar[XB_XGEN(b.x)], 1u);
;             asm volatile("s_waitcnt vmcnt(0)" ::: "memory");
;         } else {
;             XB_SPIN(xb_ld(&bar[XB_XGEN(b.x)]) == gen, bar);
;             __builtin_amdgcn_fence(__ATOMIC_ACQUIRE, "agent");
;             asm volatile("s_waitcnt vmcnt(0)" ::: "memory");
;         }
;     }
;     __syncthreads();
; }
; __global__ void __launch_bounds__(512, 2) mega(Params p) {
;     ...
;         CASE(15) sample_reduce<1>((const float*)(ws + O_SLAB), 4, nullptr, nullptr, 0.0625f * LOG2E, (const float*)(ws + O_ST2), nullptr, nullptr, (bf16_t*)(ws + O_QC), nullptr, (const float*)(ws + O_C1) + C_Q, (const float*)(ws + O_C2) + C_Q); SEAM(15)
.Lq15_prod_done:
	s_branch .LBB0_1320
	s_waitcnt vmcnt(0)
	s_waitcnt lgkmcnt(0)
	s_barrier
	s_mov_b64 s[38:39], exec
	v_readlane_b32 s0, v252, 6
	v_readlane_b32 s1, v252, 7
	s_and_b64 s[0:1], s[38:39], s[0:1]
	s_mov_b64 exec, s[0:1]
	s_cbranch_execz .LBB0_1319
	s_add_i32 s0, 0, 0x23f10
	v_mov_b32_e32 v0, s0
	s_waitcnt vmcnt(0) expcnt(0) lgkmcnt(0)
	ds_read_b32 v2, v0
	s_add_i32 s0, 0, 0x23f14
	v_mov_b32_e32 v0, s0
	ds_read_b32 v0, v0
	s_waitcnt lgkmcnt(1)
	v_cmp_ne_u32_e32 vcc, 0, v2
	s_cbranch_vccnz .LBB0_1290
	s_add_u32 s6, s52, 0x2fb43200
	s_addc_u32 s7, s53, 0
	s_add_u32 s4, s52, 0x2fb43400
	s_addc_u32 s5, s53, 0
	s_add_u32 s10, s52, 0x2fb43500
	s_addc_u32 s11, s53, 0
	s_add_u32 s12, s52, 0x2fb43600
	s_addc_u32 s13, s53, 0
	s_add_u32 s14, s52, 0x2fb43700
	s_addc_u32 s15, s53, 0
	s_add_u32 s16, s52, 0x2fb43800
	s_addc_u32 s17, s53, 0
	s_add_u32 s18, s52, 0x2fb43900
	s_addc_u32 s19, s53, 0
	s_add_u32 s20, s52, 0x2fb43a00
	s_addc_u32 s21, s53, 0
	s_add_u32 s22, s52, 0x2fb43b00
	s_addc_u32 s23, s53, 0
	s_add_u32 s24, s52, 0x2fb43c00
	s_addc_u32 s25, s53, 0
	s_add_u32 s26, s52, 0x2fb43d00
	s_addc_u32 s27, s53, 0
	s_add_u32 s28, s52, 0x2fb43e00
	s_addc_u32 s29, s53, 0
	s_add_u32 s30, s52, 0x2fb43f00
	s_addc_u32 s31, s53, 0
	s_add_u32 s34, s52, 0x2fb44000
	s_addc_u32 s35, s53, 0
	s_add_u32 s36, s52, 0x2fb44100
	s_addc_u32 s37, s53, 0
	s_add_u32 s40, s52, 0x2fb44200
	s_addc_u32 s41, s53, 0
	v_readlane_b32 s0, v252, 0
	s_add_u32 s46, s52, 0x2fb44300
	s_mul_i32 s0, s83, s0
	s_addc_u32 s47, s53, 0
	s_mul_i32 s0, s0, s82
	s_mov_b32 s1, 1
	s_mov_b64 s[8:9], 0
	s_waitcnt lgkmcnt(0)
	v_mov_b64_e32 v[0:1], s[4:5]
	v_mov_b64_e32 v[2:3], s[10:11]
	v_mov_b64_e32 v[4:5], s[12:13]
	v_mov_b64_e32 v[6:7], s[14:15]
	v_mov_b64_e32 v[8:9], s[16:17]
	v_mov_b64_e32 v[10:11], s[18:19]
	v_mov_b64_e32 v[12:13], s[20:21]
	v_mov_b64_e32 v[14:15], s[22:23]
	v_mov_b64_e32 v[16:17], s[24:25]
	v_mov_b64_e32 v[18:19], s[26:27]
	v_mov_b64_e32 v[20:21], s[28:29]
	v_mov_b64_e32 v[22:23], s[30:31]
	v_mov_b64_e32 v[24:25], s[34:35]
	v_mov_b64_e32 v[26:27], s[36:37]
	v_mov_b64_e32 v[28:29], s[40:41]
	v_mov_b64_e32 v[30:31], s[46:47]
	s_branch .LBB0_1280

; #define LAS __attribute__((address_space(3)))
; #define GASP __attribute__((address_space(1)))
; #define CA_ISSUE(tt) do { const size_t o_ = (size_t)(bb * 256 + (tt) * 64 + lrow) * D + h * 256 + lc * 32; \
;         _Pragma("unroll") for (int i_ = 0; i_ < 4; ++i_) { pf[i_] = *(const GASP u32x4*)(MKB + o_ + 8 * i_); pf[4 + i_] = *(const GASP u32x4*)(MVB + o_ + 8 * i_); } } while (0)
; #define CA_WRITE(buf) do { LAS unsigned char* kd_ = L + (buf) * CA_BUF + lrow * CA_KRS + lc * 64; LAS unsigned char* vd_ = L + (buf) * CA_BUF + CA_VOFF + lrow * CA_VRS + lc * 64; \
;         _Pragma("unroll") for (int i_ = 0; i_ < 4; ++i_) { *(LAS u32x4*)(kd_ + 16 * i_) = pf[i_]; *(LAS u32x4*)(vd_ + 16 * i_) = pf[4 + i_]; } } while (0)
; __device__ __forceinline__ void cross_unit(const Params& p, LAS unsigned char* L, int bb, int h, int qi) {
;     unsigned char* ws = p.ws;
;     int tid = threadIdx.x; asm volatile("" : "+v"(tid));
;     const int lane = tid & 63, r = lane & 31, hi = lane >> 5, wid = __builtin_amdgcn_readfirstlane(tid >> 6), sub = wid & 3, dh = wid >> 2;
;     const bf16_t* QC = (const bf16_t*)(ws + O_QC); const bf16_t* MKB = (const bf16_t*)(ws + O_MKB); const bf16_t* MVB = (const bf16_t*)(ws + O_MVB);
;     const int nq = bb < 16 ? 128 : 32, rowq0 = bb < 16 ? bb * SEQ + qi * 128 : NP + (bb - 16) * 32;
;     const bool active = sub * 32 < nq;
;     const bf16_t* qp = QC + (size_t)(rowq0 + (active ? sub * 32 : 0) + r) * D + h * 256 + hi * 8;
;     bf16x8 qf[16];
; #pragma unroll
;     for (int d0 = 0; d0 < 16; ++d0) qf[d0] = *(const GASP bf16x8*)(qp + d0 * 16);
;     f32x16 OT[4];
; #pragma unroll
;     for (int e = 0; e < 4; ++e)
; #pragma unroll
;         for (int i = 0; i < 16; ++i) OT[e][i] = 0.f;
;     float m = -1e30f, l = 0.f;
;     const int lrow = tid >> 3, lc = tid & 7;
;     u32x4 pf[8];
;     ...
;     CA_ISSUE(0); CA_WRITE(0);
; #pragma unroll
;     for (int d0 = 0; d0 < 16; ++d0) asm volatile("" : "+v"(qf[d0]));
;     __syncthreads();
; __global__ void __launch_bounds__(512, 2) mega(Params p) {
;     ...
;             for (;;) {
;                 int u = queue_next(ctr, lds);
;                 if (u >= NU_P + NU_S) break;
;                 if (u < NU_P) cross_unit(p, lds, u >> 6, (u >> 4) & 3, u & 15);
;                 else { u -= NU_P; cross_unit(p, lds, 16 + (u >> 2), u & 3, 0); }
.LBB0_1326:
	s_or_b64 exec, exec, s[16:17]
	s_waitcnt vmcnt(0) lgkmcnt(0)
	s_barrier
	ds_read_b32 v0, v220
	s_mov_b64 s[16:17], -1
	s_waitcnt lgkmcnt(0)
	s_barrier
	v_cmp_lt_i32_e32 vcc, s1, v0
	v_readfirstlane_b32 s20, v0
	s_cbranch_vccnz .LBB0_1323
	s_cmpk_gt_i32 s20, 0x3ff
	s_cbranch_scc0 .LBB0_1338
	s_add_u32 s98, s52, 0x2fb46800
	s_addc_u32 s99, s53, 0
	s_mov_b32 s101, 0
	v_mov_b32_e32 v250, 0
.Lq15_spin:
	global_load_dword v251, v250, s[98:99] sc1
	s_waitcnt vmcnt(0)
	v_readfirstlane_b32 s100, v251
	s_cmpk_gt_u32 s100, 0x7f
	s_cbranch_scc1 .Lq15_ready
	s_sleep 2
	s_add_i32 s101, s101, 1
	s_cmp_lt_u32 s101, 0x2000
	s_cbranch_scc1 .Lq15_spin
.Lq15_ready:
	buffer_inv sc1
	s_waitcnt vmcnt(0)
	s_add_i32 s14, s20, 0xfffffc00
	s_lshr_b32 s18, s14, 2
	s_add_i32 s19, s18, 16
	v_mov_b32_e32 v8, v208
	s_lshl_b32 s14, s19, 5
	v_readfirstlane_b32 s21, v8
	s_addk_i32 s14, 0x7e00
	s_and_b32 s16, s21, 0xc0
	v_and_b32_e32 v9, 31, v8
	s_cmp_eq_u32 s16, 0
	v_ashrrev_i32_e32 v11, 3, v8
	s_cselect_b64 s[16:17], -1, 0
	v_or_b32_e32 v0, s14, v9
	s_lshl_b32 s14, s20, 8
	v_lshl_add_u32 v4, s19, 8, v11
	v_lshlrev_b64 v[210:211], 11, v[0:1]
	s_and_b32 s14, s14, 0x300
	v_and_b32_e32 v0, 7, v8
	v_ashrrev_i32_e32 v5, 31, v4
	v_lshlrev_b64 v[4:5], 11, v[4:5]
	v_lshl_or_b32 v216, v0, 5, s14
	v_lshl_or_b32 v4, v216, 1, v4
	v_lshl_add_u64 v[6:7], s[8:9], 0, v[4:5]
	v_lshl_add_u64 v[4:5], s[10:11], 0, v[4:5]
	global_load_dwordx4 v[112:115], v[6:7], off offset:16
	global_load_dwordx4 v[116:119], v[6:7], off
	global_load_dwordx4 v[132:135], v[4:5], off offset:16
	global_load_dwordx4 v[148:151], v[4:5], off
	global_load_dwordx4 v[120:123], v[6:7], off offset:48
	global_load_dwordx4 v[124:127], v[6:7], off offset:32
	global_load_dwordx4 v[144:147], v[4:5], off offset:48
	global_load_dwordx4 v[160:163], v[4:5], off offset:32
	v_bfe_u32 v10, v8, 5, 1
	v_lshl_add_u64 v[2:3], s[6:7], 0, v[210:211]
	s_lshl_b32 s22, s14, 1
	s_mov_b32 s23, s15
	v_lshl_add_u64 v[2:3], v[2:3], 0, s[22:23]
	v_lshlrev_b32_e32 v214, 4, v10
	v_mov_b32_e32 v215, v1
	v_lshl_add_u64 v[2:3], v[2:3], 0, v[214:215]
	global_load_dwordx4 v[128:131], v[2:3], off
	global_load_dwordx4 v[136:139], v[2:3], off offset:32
	global_load_dwordx4 v[140:143], v[2:3], off offset:64
	global_load_dwordx4 v[152:155], v[2:3], off offset:96
	global_load_dwordx4 v[156:159], v[2:3], off offset:128
	global_load_dwordx4 v[164:167], v[2:3], off offset:160
	global_load_dwordx4 v[168:171], v[2:3], off offset:192
	global_load_dwordx4 v[172:175], v[2:3], off offset:224
	global_load_dwordx4 v[176:179], v[2:3], off offset:256
	global_load_dwordx4 v[180:183], v[2:3], off offset:288
	global_load_dwordx4 v[184:187], v[2:3], off offset:320
	global_load_dwordx4 v[188:191], v[2:3], off offset:352
	global_load_dwordx4 v[192:195], v[2:3], off offset:384
	global_load_dwordx4 v[196:199], v[2:3], off offset:416
	global_load_dwordx4 v[200:203], v[2:3], off offset:448
	global_load_dwordx4 v[204:207], v[2:3], off offset:480
	v_mul_lo_u32 v215, v11, s4
	v_lshlrev_b32_e32 v222, 6, v0
	v_add3_u32 v0, 0, v215, v222
	v_lshlrev_b32_e32 v212, 2, v10
	v_mad_u64_u32 v[2:3], s[24:25], v11, 48, v[0:1]
	v_mov_b32_e32 v14, v1
	v_mov_b32_e32 v15, v1
	v_mul_lo_u32 v223, v11, s5
	v_mul_u32_u24_e32 v226, 0x210, v9
	v_mov_b32_e32 v3, v1
	v_mov_b32_e32 v4, v1
	v_mov_b32_e32 v5, v1
	v_mov_b32_e32 v6, v1
	v_mov_b32_e32 v7, v1
	v_mov_b32_e32 v9, v1
	v_mov_b32_e32 v10, v1
	v_mov_b32_e32 v12, v1
	v_mov_b32_e32 v13, v1
	s_mov_b32 s22, 0
	s_and_b32 s23, s21, 0xffffff00
	v_mov_b32_e32 v227, 0xf149f2ca
	v_mov_b32_e32 v213, 0
	s_waitcnt vmcnt(22)
	ds_write_b128 v0, v[116:119]
	s_waitcnt vmcnt(20)
	ds_write_b128 v2, v[148:151] offset:33792
	ds_write_b128 v0, v[112:115] offset:16
	ds_write_b128 v2, v[132:135] offset:33808
	s_waitcnt vmcnt(18)
	ds_write_b128 v0, v[124:127] offset:32
	s_waitcnt vmcnt(16)
	ds_write_b128 v2, v[160:163] offset:33824
	ds_write_b128 v0, v[120:123] offset:48
	ds_write_b128 v2, v[144:147] offset:33840
	v_lshrrev_b32_e32 v0, 2, v8
	v_and_or_b32 v0, v0, 3, v212
	v_mul_u32_u24_e32 v224, 0x240, v0
	v_and_b32_e32 v0, 16, v8
	v_lshlrev_b32_e32 v2, 2, v8
	v_and_or_b32 v0, v2, 12, v0
	v_lshlrev_b32_e32 v225, 1, v0
	v_lshl_add_u32 v0, s18, 8, v11
	v_add_u32_e32 v218, 0x1040, v0
	v_mov_b32_e32 v0, v1
	v_mov_b32_e32 v2, v1
	v_mov_b32_e32 v8, v1
	v_mov_b32_e32 v11, v1
	v_mov_b64_e32 v[30:31], v[14:15]
	v_mov_b64_e32 v[46:47], v[14:15]
	v_mov_b64_e32 v[62:63], v[14:15]
	v_mov_b64_e32 v[78:79], v[14:15]
	v_mov_b64_e32 v[28:29], v[12:13]
	v_mov_b64_e32 v[26:27], v[10:11]
	v_mov_b64_e32 v[24:25], v[8:9]
	v_mov_b64_e32 v[22:23], v[6:7]
	v_mov_b64_e32 v[20:21], v[4:5]
	v_mov_b64_e32 v[18:19], v[2:3]
	v_mov_b64_e32 v[16:17], v[0:1]
	v_mov_b64_e32 v[44:45], v[12:13]
	v_mov_b64_e32 v[42:43], v[10:11]
	v_mov_b64_e32 v[40:41], v[8:9]
	v_mov_b64_e32 v[38:39], v[6:7]
	v_mov_b64_e32 v[36:37], v[4:5]
	v_mov_b64_e32 v[34:35], v[2:3]
	v_mov_b64_e32 v[32:33], v[0:1]
	v_mov_b64_e32 v[60:61], v[12:13]
	v_mov_b64_e32 v[58:59], v[10:11]
	v_mov_b64_e32 v[56:57], v[8:9]
	v_mov_b64_e32 v[54:55], v[6:7]
	v_mov_b64_e32 v[52:53], v[4:5]
	v_mov_b64_e32 v[50:51], v[2:3]
	v_mov_b64_e32 v[48:49], v[0:1]
	v_mov_b64_e32 v[76:77], v[12:13]
	v_mov_b64_e32 v[74:75], v[10:11]
	v_mov_b64_e32 v[72:73], v[8:9]
	v_mov_b64_e32 v[70:71], v[6:7]
	v_mov_b64_e32 v[68:69], v[4:5]
	v_mov_b64_e32 v[66:67], v[2:3]
	v_mov_b64_e32 v[64:65], v[0:1]
	s_waitcnt vmcnt(15)
	s_waitcnt vmcnt(14)
	s_waitcnt vmcnt(13)
	s_waitcnt vmcnt(12)
	s_waitcnt vmcnt(11)
	s_waitcnt vmcnt(10)
	s_waitcnt vmcnt(9)
	s_waitcnt vmcnt(8)
	s_waitcnt vmcnt(7)
	s_waitcnt vmcnt(6)
	s_waitcnt vmcnt(5)
	s_waitcnt vmcnt(4)
	s_waitcnt vmcnt(3)
	s_waitcnt vmcnt(2)
	s_waitcnt vmcnt(1)
	s_waitcnt vmcnt(0)
	s_waitcnt lgkmcnt(0)
	s_barrier
	s_branch .LBB0_1330

; __global__ void __launch_bounds__(512, 2) mega(Params p) {
	.amdhsa_kernel _Z4mega6Params
		.amdhsa_group_segment_fixed_size 0
		.amdhsa_private_segment_fixed_size 0
		.amdhsa_kernarg_size 552
		.amdhsa_user_sgpr_count 2
		.amdhsa_user_sgpr_dispatch_ptr 0
		.amdhsa_user_sgpr_queue_ptr 0
		.amdhsa_user_sgpr_kernarg_segment_ptr 1
		.amdhsa_user_sgpr_dispatch_id 0
		.amdhsa_user_sgpr_kernarg_preload_length 0
		.amdhsa_user_sgpr_kernarg_preload_offset 0
		.amdhsa_user_sgpr_private_segment_size 0
		.amdhsa_uses_dynamic_stack 0
		.amdhsa_enable_private_segment 0
		.amdhsa_system_sgpr_workgroup_id_x 1
		.amdhsa_system_sgpr_workgroup_id_y 0
		.amdhsa_system_sgpr_workgroup_id_z 0
		.amdhsa_system_sgpr_workgroup_info 0
		.amdhsa_system_vgpr_workitem_id 2
		.amdhsa_next_free_vgpr 253
		.amdhsa_next_free_sgpr 102
		.amdhsa_accum_offset 256
		.amdhsa_reserve_vcc 1
		.amdhsa_float_round_mode_32 0
		.amdhsa_float_round_mode_16_64 0
		.amdhsa_float_denorm_mode_32 3
		.amdhsa_float_denorm_mode_16_64 3
		.amdhsa_dx10_clamp 1
		.amdhsa_ieee_mode 1
		.amdhsa_fp16_overflow 0
		.amdhsa_tg_split 0
		.amdhsa_exception_fp_ieee_invalid_op 0
		.amdhsa_exception_fp_denorm_src 0
		.amdhsa_exception_fp_ieee_div_zero 0
		.amdhsa_exception_fp_ieee_overflow 0
		.amdhsa_exception_fp_ieee_underflow 0
		.amdhsa_exception_fp_ieee_inexact 0
		.amdhsa_exception_int_div_zero 0
	.end_amdhsa_kernel

; __global__ void __launch_bounds__(512, 2) mega(Params p) {
amdhsa.kernels:
  - .agpr_count:     0
    .args:
      - .offset:         0
        .size:           296
        .value_kind:     by_value
      - .offset:         296
        .size:           4
        .value_kind:     hidden_block_count_x
      - .offset:         300
        .size:           4
        .value_kind:     hidden_block_count_y
      - .offset:         304
        .size:           4
        .value_kind:     hidden_block_count_z
      - .offset:         308
        .size:           2
        .value_kind:     hidden_group_size_x
      - .offset:         310
        .size:           2
        .value_kind:     hidden_group_size_y
      - .offset:         312
        .size:           2
        .value_kind:     hidden_group_size_z
      - .offset:         314
        .size:           2
        .value_kind:     hidden_remainder_x
      - .offset:         316
        .size:           2
        .value_kind:     hidden_remainder_y
      - .offset:         318
        .size:           2
        .value_kind:     hidden_remainder_z
      - .offset:         336
        .size:           8
        .value_kind:     hidden_global_offset_x
      - .offset:         344
        .size:           8
        .value_kind:     hidden_global_offset_y
      - .offset:         352
        .size:           8
        .value_kind:     hidden_global_offset_z
      - .offset:         360
        .size:           2
        .value_kind:     hidden_grid_dims
      - .offset:         384
        .size:           8
        .value_kind:     hidden_multigrid_sync_arg
      - .offset:         416
        .size:           4
        .value_kind:     hidden_dynamic_lds_size
    .group_segment_fixed_size: 0
    .kernarg_segment_align: 8
    .kernarg_segment_size: 552
    .language:       OpenCL C
    .language_version:
      - 2
      - 0
    .max_flat_workgroup_size: 512
    .name:           _Z4mega6Params
    .private_segment_fixed_size: 0
    .sgpr_count:     108
    .sgpr_spill_count: 24
    .symbol:         _Z4mega6Params.kd
    .uniform_work_group_size: 1
    .uses_dynamic_stack: false
    .vgpr_count:     253
    .vgpr_spill_count: 0
    .wavefront_size: 64
